# prep phase: second-pass MoBA gating items take the mirrored chunk so every wave does the same number of gate iterations
# speedup vs baseline: 1.0396x; 1.0036x over previous
; __device__ __forceinline__ float bflo(unsigned w) { return __uint_as_float(w << 16); }
; __device__ __forceinline__ float bfhi(unsigned w) { return __uint_as_float(w & 0xffff0000u); }
; __device__ __forceinline__ void prep_phase(const Args& a, LAS unsigned char* lds, int tid, int lane, int wave) {
;     ...
;     for (int wv = BID * NWAVES + wave; wv < Bn * 8 * (S / 64); wv += nwv) {
;         const int bh = __builtin_amdgcn_readfirstlane(wv / (S / 64)), t0 = __builtin_amdgcn_readfirstlane((wv % (S / 64)) * 64);
;         const int b = bh >> 3, h = bh & 7, t = t0 + lane, blk = t0 >> 8;
;         unsigned mask = 1u << blk;
;         if (blk > 0) {
;             float q[64];
;             const v4u* qp = (const v4u*)(Q + ((size_t)(b * S + t)) * D + h * 64);
; #pragma unroll
;             for (int c = 0; c < 8; ++c) { const v4u w = qp[c]; q[8 * c] = bflo(w.x); q[8 * c + 1] = bfhi(w.x); q[8 * c + 2] = bflo(w.y); q[8 * c + 3] = bfhi(w.y); q[8 * c + 4] = bflo(w.z); q[8 * c + 5] = bfhi(w.z); q[8 * c + 6] = bflo(w.w); q[8 * c + 7] = bfhi(w.w); }
;             float g0 = -3e38f, g1 = -3e38f, g2 = -3e38f; int i0 = -1, i1 = -1, i2 = -1;
.LBB0_559:
	s_ashr_i32 s6, s3, 31
	s_lshr_b32 s6, s6, 25
	s_add_i32 s6, s3, s6
	s_ashr_i32 s12, s6, 7
	s_and_b32 s6, s6, 0xffffff80
	s_sub_i32 s10, s3, s6
	s_sub_i32 s98, 0x7f, s10
	s_cmpk_lt_i32 s3, 0x800
	s_cselect_b32 s10, s10, s98
	s_ashr_i32 s11, s10, 2
	s_lshl_b32 s13, 1, s11
	s_cmp_gt_i32 s11, 0
	v_lshl_or_b32 v0, s10, 6, v12
	s_cselect_b64 s[22:23], -1, 0
	s_cmp_lt_i32 s11, 1
	v_mov_b32_e32 v2, s13
	s_cbranch_scc1 .LBB0_570
	s_lshl_b32 s6, s12, 10
	s_and_b32 s6, s6, 0xffffe000
	v_add_u32_e32 v2, s6, v0
	s_waitcnt lgkmcnt(1)
	v_ashrrev_i32_e32 v3, 31, v2
	v_lshlrev_b64 v[2:3], 11, v[2:3]
	s_lshl_b32 s6, s12, 7
	v_lshl_add_u64 v[2:3], s[4:5], 0, v[2:3]
	s_and_b32 s6, s6, 0x380
	v_lshl_add_u64 v[10:11], v[2:3], 0, s[6:7]
	global_load_dwordx4 v[2:5], v[10:11], off
	global_load_dwordx4 v[6:9], v[10:11], off offset:16
	global_load_dwordx4 v[36:39], v[10:11], off offset:32
	global_load_dwordx4 v[46:49], v[10:11], off offset:48
	global_load_dwordx4 v[54:57], v[10:11], off offset:64
	global_load_dwordx4 v[62:65], v[10:11], off offset:80
	global_load_dwordx4 v[68:71], v[10:11], off offset:96
	global_load_dwordx4 v[72:75], v[10:11], off offset:112
	s_lshl_b32 s8, s12, 5
	s_ashr_i32 s9, s8, 31
	s_lshl_b64 s[8:9], s[8:9], 8
	s_add_u32 s24, s19, s8
	v_mov_b32_e32 v50, 0xff61b1e6
	v_mov_b32_e32 v44, -1
	s_addc_u32 s25, s20, s9
	s_mov_b32 s6, 0
	s_waitcnt vmcnt(7) lgkmcnt(0)
	v_lshlrev_b32_e32 v1, 16, v2
	v_and_b32_e32 v17, 0xffff0000, v2
	v_lshlrev_b32_e32 v18, 16, v3
	v_and_b32_e32 v19, 0xffff0000, v3
	v_lshlrev_b32_e32 v20, 16, v4
	v_and_b32_e32 v21, 0xffff0000, v4
	v_lshlrev_b32_e32 v22, 16, v5
	v_and_b32_e32 v23, 0xffff0000, v5
	s_waitcnt vmcnt(6)
	v_lshlrev_b32_e32 v24, 16, v6
	v_and_b32_e32 v25, 0xffff0000, v6
	v_lshlrev_b32_e32 v26, 16, v7
	v_and_b32_e32 v27, 0xffff0000, v7
	v_lshlrev_b32_e32 v28, 16, v8
	v_and_b32_e32 v29, 0xffff0000, v8
	v_lshlrev_b32_e32 v30, 16, v9
	v_and_b32_e32 v31, 0xffff0000, v9
	s_waitcnt vmcnt(5)
	v_lshlrev_b32_e32 v32, 16, v36
	v_and_b32_e32 v33, 0xffff0000, v36
	v_lshlrev_b32_e32 v34, 16, v37
	v_and_b32_e32 v35, 0xffff0000, v37
	v_lshlrev_b32_e32 v36, 16, v38
	v_and_b32_e32 v37, 0xffff0000, v38
	v_lshlrev_b32_e32 v38, 16, v39
	v_and_b32_e32 v39, 0xffff0000, v39
	s_waitcnt vmcnt(4)
	v_lshlrev_b32_e32 v40, 16, v46
	v_and_b32_e32 v41, 0xffff0000, v46
	v_lshlrev_b32_e32 v42, 16, v47
	v_and_b32_e32 v43, 0xffff0000, v47
	v_lshlrev_b32_e32 v45, 16, v48
	v_and_b32_e32 v46, 0xffff0000, v48
	v_lshlrev_b32_e32 v47, 16, v49
	v_and_b32_e32 v48, 0xffff0000, v49
	s_waitcnt vmcnt(3)
	v_lshlrev_b32_e32 v49, 16, v54
	v_and_b32_e32 v51, 0xffff0000, v54
	v_lshlrev_b32_e32 v52, 16, v55
	v_and_b32_e32 v53, 0xffff0000, v55
	v_lshlrev_b32_e32 v54, 16, v56
	v_and_b32_e32 v55, 0xffff0000, v56
	v_lshlrev_b32_e32 v56, 16, v57
	v_and_b32_e32 v57, 0xffff0000, v57
	s_waitcnt vmcnt(2)
	v_lshlrev_b32_e32 v58, 16, v62
	v_and_b32_e32 v59, 0xffff0000, v62
	v_lshlrev_b32_e32 v60, 16, v63
	v_and_b32_e32 v61, 0xffff0000, v63
	v_lshlrev_b32_e32 v62, 16, v64
	v_and_b32_e32 v63, 0xffff0000, v64
	v_lshlrev_b32_e32 v64, 16, v65
	v_and_b32_e32 v65, 0xffff0000, v65
	s_waitcnt vmcnt(1)
	v_lshlrev_b32_e32 v66, 16, v68
	v_and_b32_e32 v67, 0xffff0000, v68
	v_lshlrev_b32_e32 v68, 16, v69
	v_and_b32_e32 v69, 0xffff0000, v69
	v_lshlrev_b32_e32 v2, 16, v70
	v_and_b32_e32 v3, 0xffff0000, v70
	v_lshlrev_b32_e32 v4, 16, v71
	v_and_b32_e32 v5, 0xffff0000, v71
	s_waitcnt vmcnt(0)
	v_lshlrev_b32_e32 v6, 16, v72
	v_and_b32_e32 v7, 0xffff0000, v72
	v_lshlrev_b32_e32 v8, 16, v73
	v_and_b32_e32 v9, 0xffff0000, v73
	v_lshlrev_b32_e32 v10, 16, v74
	v_and_b32_e32 v11, 0xffff0000, v74
	v_lshlrev_b32_e32 v14, 16, v75
	v_and_b32_e32 v15, 0xffff0000, v75
	v_mov_b32_e32 v70, -1
	v_mov_b32_e32 v71, -1
	v_mov_b32_e32 v72, 0xff61b1e6
	v_mov_b32_e32 v73, 0xff61b1e6
